# stack (v67) + rotating merge-tile preload, next preload issued mid-seam (latency hidden under the remaining seam VALU)
# speedup vs baseline: 1.0029x; 1.0029x over previous
; __device__ __forceinline__ f32x4 un_unorm8(unsigned w) { return (f32x4){fmaxf((float)(w & 255u), 0.5f), fmaxf((float)((w >> 8) & 255u), 0.5f), fmaxf((float)((w >> 16) & 255u), 0.5f), fmaxf((float)(w >> 24), 0.5f)}; }
;     __device__ __forceinline__ void seam(f32x4 (&acc)[2][2][4][2], const Unit& u, int n, int wr, int wc, int fr, int fq) const {
;     ...
;             for (int m = 0; m < 4; ++m)
; #pragma unroll
;                 for (int bj = 0; bj < 2; ++bj) { const f32x4 a0 = un_unorm8(ga[m][bj].x), a1 = un_unorm8(ga[m][bj].y), b0 = un_unorm8(gb[m][bj].x), b1 = un_unorm8(gb[m][bj].y);
; #pragma unroll
;                     for (int j = 0; j < 4; ++j) { acc[ai][bj][m][0][j] *= a0[j] * __builtin_amdgcn_rcpf(b0[j]); acc[ai][bj][m][1][j] *= a1[j] * __builtin_amdgcn_rcpf(b1[j]); } }
.Lsm_a:
	v_cvt_f32_ubyte0_e32 v212, v192
	v_cvt_f32_ubyte1_e32 v213, v192
	v_cvt_f32_ubyte2_e32 v214, v192
	v_cvt_f32_ubyte0_e32 v219, v195
	v_cvt_f32_ubyte3_e32 v184, v192
	v_cvt_f32_ubyte3_e32 v218, v194
	v_max_f32_e32 v225, 0.5, v214
	v_max_f32_e32 v214, 0.5, v219
	v_max_f32_e32 v219, 0.5, v184
	v_cvt_f32_ubyte0_e32 v184, v193
	v_cvt_f32_ubyte2_e32 v217, v194
	v_cvt_f32_ubyte3_e32 v222, v195
	v_max_f32_e32 v224, 0.5, v213
	v_max_f32_e32 v213, 0.5, v218
	v_max_f32_e32 v218, 0.5, v184
	v_cvt_f32_ubyte1_e32 v184, v193
	v_max_f32_e32 v223, 0.5, v212
	v_max_f32_e32 v212, 0.5, v217
	v_max_f32_e32 v217, 0.5, v222
	v_max_f32_e32 v222, 0.5, v184
	v_cvt_f32_ubyte2_e32 v184, v193
	v_cvt_f32_ubyte0_e32 v215, v194
	v_cvt_f32_ubyte1_e32 v216, v194
	v_cvt_f32_ubyte1_e32 v220, v195
	v_cvt_f32_ubyte2_e32 v221, v195
	v_max_f32_e32 v226, 0.5, v184
	v_cvt_f32_ubyte3_e32 v184, v193
	v_max_f32_e32 v186, 0.5, v215
	v_max_f32_e32 v187, 0.5, v216
	v_max_f32_e32 v215, 0.5, v220
	v_max_f32_e32 v216, 0.5, v221
	v_max_f32_e32 v227, 0.5, v184
	v_rcp_f32_e32 v184, v223
	v_rcp_f32_e32 v185, v224
	v_rcp_f32_e32 v220, v225
	v_rcp_f32_e32 v221, v219
	v_rcp_f32_e32 v218, v218
	v_rcp_f32_e32 v219, v222
	v_rcp_f32_e32 v222, v226
	v_rcp_f32_e32 v223, v227
	v_pk_mul_f32 v[184:185], v[186:187], v[184:185]
	v_pk_mul_f32 v[186:187], v[212:213], v[220:221]
	v_pk_mul_f32 v[128:129], v[128:129], v[184:185]
	v_pk_mul_f32 v[130:131], v[130:131], v[186:187]
	v_pk_mul_f32 v[184:185], v[214:215], v[218:219]
	v_pk_mul_f32 v[186:187], v[216:217], v[222:223]
	v_cvt_f32_ubyte0_e32 v214, v196
	v_cvt_f32_ubyte1_e32 v215, v196
	v_cvt_f32_ubyte2_e32 v216, v196
	v_cvt_f32_ubyte3_e32 v208, v196
	v_max_f32_e32 v217, 0.5, v208
	v_cvt_f32_ubyte0_e32 v208, v197
	v_max_f32_e32 v218, 0.5, v208
	v_cvt_f32_ubyte1_e32 v208, v197
	v_max_f32_e32 v219, 0.5, v208
	v_cvt_f32_ubyte2_e32 v208, v197
	v_max_f32_e32 v214, 0.5, v214
	v_max_f32_e32 v215, 0.5, v215
	v_max_f32_e32 v216, 0.5, v216
	v_max_f32_e32 v220, 0.5, v208
	v_cvt_f32_ubyte3_e32 v208, v197
	v_max_f32_e32 v221, 0.5, v208
	v_rcp_f32_e32 v208, v214
	v_rcp_f32_e32 v209, v215
	v_rcp_f32_e32 v216, v216
	v_rcp_f32_e32 v217, v217
	v_pk_mul_f32 v[126:127], v[126:127], v[186:187]
	v_pk_mul_f32 v[124:125], v[124:125], v[184:185]
	v_cvt_f32_ubyte0_e32 v184, v198
	v_cvt_f32_ubyte1_e32 v185, v198
	v_cvt_f32_ubyte2_e32 v186, v198
	v_cvt_f32_ubyte3_e32 v187, v198
	v_cvt_f32_ubyte0_e32 v210, v199
	v_rcp_f32_e32 v214, v218
	v_rcp_f32_e32 v215, v219
	v_rcp_f32_e32 v218, v220
	v_rcp_f32_e32 v219, v221
	v_max_f32_e32 v212, 0.5, v210
	v_cvt_f32_ubyte1_e32 v210, v199
	v_max_f32_e32 v184, 0.5, v184
	v_max_f32_e32 v185, 0.5, v185
	v_max_f32_e32 v186, 0.5, v186
	v_max_f32_e32 v187, 0.5, v187
	v_max_f32_e32 v213, 0.5, v210
	v_cvt_f32_ubyte2_e32 v210, v199
	v_cvt_f32_ubyte3_e32 v211, v199
	v_max_f32_e32 v210, 0.5, v210
	v_max_f32_e32 v211, 0.5, v211
	v_pk_mul_f32 v[184:185], v[184:185], v[208:209]
	v_pk_mul_f32 v[186:187], v[186:187], v[216:217]
	v_pk_mul_f32 v[120:121], v[120:121], v[184:185]
	v_pk_mul_f32 v[122:123], v[122:123], v[186:187]
	v_pk_mul_f32 v[184:185], v[212:213], v[214:215]
	v_pk_mul_f32 v[186:187], v[210:211], v[218:219]
	v_cvt_f32_ubyte0_e32 v210, v200
	v_cvt_f32_ubyte1_e32 v211, v200
	v_cvt_f32_ubyte2_e32 v212, v200
	v_cvt_f32_ubyte3_e32 v176, v200
	v_max_f32_e32 v213, 0.5, v176
	v_cvt_f32_ubyte0_e32 v176, v201
	v_max_f32_e32 v214, 0.5, v176
	v_cvt_f32_ubyte1_e32 v176, v201
	v_max_f32_e32 v215, 0.5, v176
	v_cvt_f32_ubyte2_e32 v176, v201
	v_max_f32_e32 v210, 0.5, v210
	v_max_f32_e32 v211, 0.5, v211
	v_max_f32_e32 v216, 0.5, v176
	v_cvt_f32_ubyte3_e32 v176, v201
	v_max_f32_e32 v212, 0.5, v212
	v_max_f32_e32 v217, 0.5, v176
	v_rcp_f32_e32 v176, v210
	v_rcp_f32_e32 v177, v211
	v_pk_mul_f32 v[118:119], v[118:119], v[186:187]
	v_pk_mul_f32 v[116:117], v[116:117], v[184:185]
	v_cvt_f32_ubyte0_e32 v184, v202
	v_cvt_f32_ubyte1_e32 v185, v202
	v_cvt_f32_ubyte2_e32 v186, v202
	v_cvt_f32_ubyte3_e32 v178, v202
	v_rcp_f32_e32 v210, v214
	v_rcp_f32_e32 v212, v212
	v_rcp_f32_e32 v213, v213
	v_rcp_f32_e32 v211, v215
	v_max_f32_e32 v187, 0.5, v178
	v_cvt_f32_ubyte0_e32 v178, v203
	v_max_f32_e32 v184, 0.5, v184
	v_max_f32_e32 v185, 0.5, v185
	v_max_f32_e32 v208, 0.5, v178
	v_cvt_f32_ubyte1_e32 v178, v203
	v_max_f32_e32 v186, 0.5, v186
	v_max_f32_e32 v209, 0.5, v178
	v_pk_mul_f32 v[176:177], v[184:185], v[176:177]
	v_pk_mul_f32 v[184:185], v[186:187], v[212:213]
	v_pk_mul_f32 v[112:113], v[112:113], v[176:177]
	v_pk_mul_f32 v[176:177], v[208:209], v[210:211]
	v_cvt_f32_ubyte0_e32 v186, v204
	v_cvt_f32_ubyte1_e32 v187, v204
	v_cvt_f32_ubyte2_e32 v208, v204
	v_cvt_f32_ubyte3_e32 v172, v204
	v_rcp_f32_e32 v214, v216
	v_rcp_f32_e32 v215, v217
	v_max_f32_e32 v209, 0.5, v172
	v_cvt_f32_ubyte0_e32 v172, v205
	v_max_f32_e32 v210, 0.5, v172
	v_cvt_f32_ubyte1_e32 v172, v205
	v_cvt_f32_ubyte2_e32 v178, v203
	v_cvt_f32_ubyte3_e32 v179, v203
	v_max_f32_e32 v211, 0.5, v172
	v_cvt_f32_ubyte2_e32 v172, v205
	v_max_f32_e32 v178, 0.5, v178
	v_max_f32_e32 v179, 0.5, v179
	v_max_f32_e32 v186, 0.5, v186
	v_max_f32_e32 v187, 0.5, v187
	v_max_f32_e32 v212, 0.5, v172
	v_cvt_f32_ubyte3_e32 v172, v205
	v_pk_mul_f32 v[178:179], v[178:179], v[214:215]
	v_max_f32_e32 v208, 0.5, v208
	v_max_f32_e32 v213, 0.5, v172
	v_rcp_f32_e32 v172, v186
	v_rcp_f32_e32 v173, v187
	v_pk_mul_f32 v[110:111], v[110:111], v[178:179]
	v_pk_mul_f32 v[108:109], v[108:109], v[176:177]
	v_cvt_f32_ubyte0_e32 v176, v206
	v_cvt_f32_ubyte1_e32 v177, v206
	v_cvt_f32_ubyte2_e32 v178, v206
	v_cvt_f32_ubyte3_e32 v174, v206
	v_rcp_f32_e32 v186, v210
	v_rcp_f32_e32 v208, v208
	v_rcp_f32_e32 v209, v209
	v_rcp_f32_e32 v187, v211
	v_max_f32_e32 v179, 0.5, v174
	v_cvt_f32_ubyte0_e32 v174, v207
	v_pk_mul_f32 v[114:115], v[114:115], v[184:185]
	v_max_f32_e32 v176, 0.5, v176
	v_max_f32_e32 v177, 0.5, v177
	v_max_f32_e32 v184, 0.5, v174
	v_cvt_f32_ubyte1_e32 v174, v207
	v_max_f32_e32 v178, 0.5, v178
	v_max_f32_e32 v185, 0.5, v174
	v_pk_mul_f32 v[172:173], v[176:177], v[172:173]
	v_pk_mul_f32 v[176:177], v[178:179], v[208:209]
	v_pk_mul_f32 v[104:105], v[104:105], v[172:173]
	v_pk_mul_f32 v[172:173], v[184:185], v[186:187]
	s_waitcnt vmcnt(0)
	v_cvt_f32_ubyte0_e32 v178, v168
	v_cvt_f32_ubyte1_e32 v179, v168
	v_cvt_f32_ubyte2_e32 v184, v168
	v_cvt_f32_ubyte3_e32 v168, v168
	v_rcp_f32_e32 v210, v212
	v_rcp_f32_e32 v211, v213
	v_max_f32_e32 v185, 0.5, v168
	v_cvt_f32_ubyte0_e32 v168, v169
	v_max_f32_e32 v186, 0.5, v168
	v_cvt_f32_ubyte1_e32 v168, v169
	v_cvt_f32_ubyte2_e32 v174, v207
	v_cvt_f32_ubyte3_e32 v175, v207
	s_cmp_eq_u32 s56, 0
	s_cbranch_scc0 .Lspre_e
;     __device__ __forceinline__ void seam(f32x4 (&acc)[2][2][4][2], const Unit& u, int n, int wr, int wc, int fr, int fq) const {
;     ...
;                 for (int bj = 0; bj < 2; ++bj) { const int row = u.pm * 256 + ai * 128 + wr * 64 + m * 16 + fr, col = u.pn * 256 + bj * 128 + wc * 32 + 8 * fq;
;                     const unsigned char* gp = (const unsigned char*)P + (size_t)row * ROWB + GATE_B0 + n * DM + col; ga[m][bj] = *(const u32x2*)gp; gb[m][bj] = *(const u32x2*)(gp + DM); }
	s_lshr_b32 s98, s42, 7
	s_bfe_u32 s99, s42, 0x10006
	s_or_b32 s98, s98, s99
	s_add_i32 s98, s98, s8
	s_add_i32 s98, s98, s20
	s_mul_i32 s98, s98, 0x4800
	s_add_u32 s98, s68, s98
	s_addc_u32 s99, s69, 0
	s_add_u32 s98, s98, 0x3800
	s_addc_u32 s99, s99, 0
	global_load_dwordx2 v[192:193], v254, s[98:99] offset:2048
	global_load_dwordx2 v[194:195], v254, s[98:99]
	global_load_dwordx2 v[196:197], v254, s[98:99] offset:3072
	global_load_dwordx2 v[198:199], v254, s[98:99] offset:1024
	s_add_u32 s98, s98, 0x48000
	s_addc_u32 s99, s99, 0
	global_load_dwordx2 v[200:201], v254, s[98:99] offset:2048
	global_load_dwordx2 v[202:203], v254, s[98:99]
	global_load_dwordx2 v[204:205], v254, s[98:99] offset:3072
	global_load_dwordx2 v[206:207], v254, s[98:99] offset:1024
	s_branch .Lspre_x

; __device__ __forceinline__ f32x4 un_unorm8(unsigned w) { return (f32x4){fmaxf((float)(w & 255u), 0.5f), fmaxf((float)((w >> 8) & 255u), 0.5f), fmaxf((float)((w >> 16) & 255u), 0.5f), fmaxf((float)(w >> 24), 0.5f)}; }
;     __device__ __forceinline__ void seam(f32x4 (&acc)[2][2][4][2], const Unit& u, int n, int wr, int wc, int fr, int fq) const {
;     ...
;             for (int m = 0; m < 4; ++m)
; #pragma unroll
;                 for (int bj = 0; bj < 2; ++bj) { const f32x4 a0 = un_unorm8(ga[m][bj].x), a1 = un_unorm8(ga[m][bj].y), b0 = un_unorm8(gb[m][bj].x), b1 = un_unorm8(gb[m][bj].y);
; #pragma unroll
;                     for (int j = 0; j < 4; ++j) { acc[ai][bj][m][0][j] *= a0[j] * __builtin_amdgcn_rcpf(b0[j]); acc[ai][bj][m][1][j] *= a1[j] * __builtin_amdgcn_rcpf(b1[j]); } }
.Lspre_x:
	v_max_f32_e32 v187, 0.5, v168
	v_cvt_f32_ubyte2_e32 v168, v169
	v_max_f32_e32 v174, 0.5, v174
	v_max_f32_e32 v175, 0.5, v175
	v_max_f32_e32 v178, 0.5, v178
	v_max_f32_e32 v179, 0.5, v179
	v_max_f32_e32 v208, 0.5, v168
	v_cvt_f32_ubyte3_e32 v168, v169
	v_pk_mul_f32 v[174:175], v[174:175], v[210:211]
	v_max_f32_e32 v184, 0.5, v184
	v_max_f32_e32 v209, 0.5, v168
	v_rcp_f32_e32 v168, v178
	v_rcp_f32_e32 v169, v179
	v_pk_mul_f32 v[102:103], v[102:103], v[174:175]
	v_pk_mul_f32 v[100:101], v[100:101], v[172:173]
	v_cvt_f32_ubyte0_e32 v172, v170
	v_cvt_f32_ubyte1_e32 v173, v170
	v_cvt_f32_ubyte2_e32 v174, v170
	v_cvt_f32_ubyte3_e32 v170, v170
	v_rcp_f32_e32 v178, v186
	v_rcp_f32_e32 v184, v184
	v_rcp_f32_e32 v185, v185
	v_rcp_f32_e32 v179, v187
	v_max_f32_e32 v175, 0.5, v170
	v_cvt_f32_ubyte0_e32 v170, v171
	v_pk_mul_f32 v[106:107], v[106:107], v[176:177]
	v_max_f32_e32 v172, 0.5, v172
	v_max_f32_e32 v173, 0.5, v173
	v_max_f32_e32 v176, 0.5, v170
	v_cvt_f32_ubyte1_e32 v170, v171
	v_max_f32_e32 v174, 0.5, v174
	v_max_f32_e32 v177, 0.5, v170
	v_pk_mul_f32 v[168:169], v[172:173], v[168:169]
	v_pk_mul_f32 v[172:173], v[174:175], v[184:185]
	v_pk_mul_f32 v[96:97], v[96:97], v[168:169]
	v_pk_mul_f32 v[168:169], v[176:177], v[178:179]
	v_cvt_f32_ubyte0_e32 v174, v158
	v_cvt_f32_ubyte1_e32 v175, v158
	v_cvt_f32_ubyte2_e32 v176, v158
	v_cvt_f32_ubyte3_e32 v158, v158
	v_rcp_f32_e32 v186, v208
	v_rcp_f32_e32 v187, v209
	v_max_f32_e32 v177, 0.5, v158
	v_cvt_f32_ubyte0_e32 v158, v159
	v_max_f32_e32 v178, 0.5, v158
	v_cvt_f32_ubyte1_e32 v158, v159
	v_cvt_f32_ubyte2_e32 v170, v171
	v_cvt_f32_ubyte3_e32 v171, v171
	v_max_f32_e32 v179, 0.5, v158
	v_cvt_f32_ubyte2_e32 v158, v159
	v_max_f32_e32 v170, 0.5, v170
	v_max_f32_e32 v171, 0.5, v171
	v_max_f32_e32 v174, 0.5, v174
	v_max_f32_e32 v175, 0.5, v175
	v_max_f32_e32 v184, 0.5, v158
	v_cvt_f32_ubyte3_e32 v158, v159
	v_pk_mul_f32 v[170:171], v[170:171], v[186:187]
	v_max_f32_e32 v176, 0.5, v176
	v_max_f32_e32 v185, 0.5, v158
	v_rcp_f32_e32 v158, v174
	v_rcp_f32_e32 v159, v175
	v_pk_mul_f32 v[94:95], v[94:95], v[170:171]
	v_pk_mul_f32 v[92:93], v[92:93], v[168:169]
	v_cvt_f32_ubyte0_e32 v168, v160
	v_cvt_f32_ubyte1_e32 v169, v160
	v_cvt_f32_ubyte2_e32 v170, v160
	v_cvt_f32_ubyte3_e32 v160, v160
	v_rcp_f32_e32 v174, v178
	v_rcp_f32_e32 v176, v176
	v_rcp_f32_e32 v177, v177
	v_rcp_f32_e32 v175, v179
	v_max_f32_e32 v171, 0.5, v160
	v_cvt_f32_ubyte0_e32 v160, v161
	v_pk_mul_f32 v[98:99], v[98:99], v[172:173]
	v_max_f32_e32 v168, 0.5, v168
	v_max_f32_e32 v169, 0.5, v169
	v_max_f32_e32 v172, 0.5, v160
	v_cvt_f32_ubyte1_e32 v160, v161
	v_max_f32_e32 v170, 0.5, v170
	v_max_f32_e32 v173, 0.5, v160
	v_pk_mul_f32 v[158:159], v[168:169], v[158:159]
	v_pk_mul_f32 v[168:169], v[170:171], v[176:177]
	v_pk_mul_f32 v[88:89], v[88:89], v[158:159]
	v_pk_mul_f32 v[158:159], v[172:173], v[174:175]
	v_cvt_f32_ubyte0_e32 v170, v154
	v_cvt_f32_ubyte1_e32 v171, v154
	v_cvt_f32_ubyte2_e32 v172, v154
	v_cvt_f32_ubyte3_e32 v154, v154
	v_max_f32_e32 v173, 0.5, v154
	v_cvt_f32_ubyte0_e32 v154, v155
	v_rcp_f32_e32 v178, v184
	v_rcp_f32_e32 v179, v185
	v_max_f32_e32 v174, 0.5, v154
	v_cvt_f32_ubyte1_e32 v154, v155
	v_max_f32_e32 v175, 0.5, v154
	v_cvt_f32_ubyte2_e32 v154, v155
	v_cvt_f32_ubyte2_e32 v160, v161
	v_cvt_f32_ubyte3_e32 v161, v161
	v_max_f32_e32 v170, 0.5, v170
	v_max_f32_e32 v171, 0.5, v171
	v_max_f32_e32 v172, 0.5, v172
	v_max_f32_e32 v176, 0.5, v154
	v_cvt_f32_ubyte3_e32 v154, v155
	v_max_f32_e32 v160, 0.5, v160
	v_max_f32_e32 v161, 0.5, v161
	v_max_f32_e32 v177, 0.5, v154
	v_rcp_f32_e32 v154, v170
	v_rcp_f32_e32 v155, v171
	v_rcp_f32_e32 v172, v172
	v_rcp_f32_e32 v173, v173
	v_pk_mul_f32 v[160:161], v[160:161], v[178:179]
	v_pk_mul_f32 v[84:85], v[84:85], v[158:159]
	v_pk_mul_f32 v[86:87], v[86:87], v[160:161]
	v_cvt_f32_ubyte0_e32 v158, v156
	v_cvt_f32_ubyte1_e32 v159, v156
	v_cvt_f32_ubyte2_e32 v160, v156
	v_cvt_f32_ubyte3_e32 v156, v156
	v_max_f32_e32 v158, 0.5, v158
	v_max_f32_e32 v159, 0.5, v159
	v_max_f32_e32 v160, 0.5, v160
	v_max_f32_e32 v161, 0.5, v156
	v_rcp_f32_e32 v170, v174
	v_rcp_f32_e32 v171, v175
	v_cvt_f32_ubyte0_e32 v156, v157
	v_pk_mul_f32 v[154:155], v[158:159], v[154:155]
	v_pk_mul_f32 v[158:159], v[160:161], v[172:173]
	v_mad_i64_i32 v[160:161], s[4:5], v1, s33, v[148:149]
	v_pk_mul_f32 v[90:91], v[90:91], v[168:169]
	v_max_f32_e32 v168, 0.5, v156
	v_cvt_f32_ubyte1_e32 v156, v157
	v_lshl_add_u64 v[160:161], v[160:161], 0, s[56:57]
	v_max_f32_e32 v169, 0.5, v156
	v_lshl_add_u64 v[160:161], v[160:161], 0, v[2:3]
	v_pk_mul_f32 v[80:81], v[80:81], v[154:155]
	v_pk_mul_f32 v[154:155], v[168:169], v[170:171]
	v_add_co_u32_e32 v168, vcc, s12, v160
	v_rcp_f32_e32 v174, v176
	s_nop 0
	v_addc_co_u32_e32 v169, vcc, 0, v161, vcc
	global_load_dwordx2 v[172:173], v[168:169], off
	v_rcp_f32_e32 v175, v177
	v_cvt_f32_ubyte2_e32 v156, v157
	v_cvt_f32_ubyte3_e32 v157, v157
	v_max_f32_e32 v156, 0.5, v156
	v_max_f32_e32 v157, 0.5, v157
	v_lshl_add_u64 v[160:161], v[160:161], 0, s[64:65]
	v_pk_mul_f32 v[156:157], v[156:157], v[174:175]
	global_load_dwordx2 v[174:175], v[160:161], off offset:2048
	v_cvt_f32_ubyte0_e32 v168, v150
	v_cvt_f32_ubyte1_e32 v169, v150
	v_cvt_f32_ubyte2_e32 v170, v150
	v_cvt_f32_ubyte3_e32 v150, v150
	v_max_f32_e32 v171, 0.5, v150
	v_cvt_f32_ubyte0_e32 v150, v151
	v_max_f32_e32 v176, 0.5, v150
	v_cvt_f32_ubyte1_e32 v150, v151
	v_max_f32_e32 v177, 0.5, v150
	v_cvt_f32_ubyte2_e32 v150, v151
	v_max_f32_e32 v178, 0.5, v150
	v_cvt_f32_ubyte3_e32 v150, v151
	v_pk_mul_f32 v[78:79], v[78:79], v[156:157]
	v_pk_mul_f32 v[76:77], v[76:77], v[154:155]
	v_cvt_f32_ubyte0_e32 v154, v152
	v_cvt_f32_ubyte1_e32 v155, v152
; __device__ __forceinline__ f32x4 un_unorm8(unsigned w) { return (f32x4){fmaxf((float)(w & 255u), 0.5f), fmaxf((float)((w >> 8) & 255u), 0.5f), fmaxf((float)((w >> 16) & 255u), 0.5f), fmaxf((float)(w >> 24), 0.5f)}; }
;     __device__ __forceinline__ void seam(f32x4 (&acc)[2][2][4][2], const Unit& u, int n, int wr, int wc, int fr, int fq) const {
;     ...
;         for (int ai = 0; ai < 2; ++ai) {
;             u32x2 ga[4][2], gb[4][2];
; #pragma unroll
;             for (int m = 0; m < 4; ++m)
; #pragma unroll
;                 for (int bj = 0; bj < 2; ++bj) { const int row = u.pm * 256 + ai * 128 + wr * 64 + m * 16 + fr, col = u.pn * 256 + bj * 128 + wc * 32 + 8 * fq;
;                     const unsigned char* gp = (const unsigned char*)P + (size_t)row * ROWB + GATE_B0 + n * DM + col; ga[m][bj] = *(const u32x2*)gp; gb[m][bj] = *(const u32x2*)(gp + DM); }
; #pragma unroll
;             for (int m = 0; m < 4; ++m)
; #pragma unroll
;                 for (int bj = 0; bj < 2; ++bj) { const f32x4 a0 = un_unorm8(ga[m][bj].x), a1 = un_unorm8(ga[m][bj].y), b0 = un_unorm8(gb[m][bj].x), b1 = un_unorm8(gb[m][bj].y);
; #pragma unroll
;                     for (int j = 0; j < 4; ++j) { acc[ai][bj][m][0][j] *= a0[j] * __builtin_amdgcn_rcpf(b0[j]); acc[ai][bj][m][1][j] *= a1[j] * __builtin_amdgcn_rcpf(b1[j]); } }
	v_cvt_f32_ubyte2_e32 v156, v152
	v_cvt_f32_ubyte3_e32 v152, v152
	v_max_f32_e32 v168, 0.5, v168
	v_max_f32_e32 v169, 0.5, v169
	v_max_f32_e32 v179, 0.5, v150
	v_max_f32_e32 v157, 0.5, v152
	v_cvt_f32_ubyte0_e32 v152, v153
	v_rcp_f32_e32 v150, v168
	v_rcp_f32_e32 v168, v176
	v_rcp_f32_e32 v151, v169
	v_rcp_f32_e32 v169, v177
	v_rcp_f32_e32 v176, v178
	v_rcp_f32_e32 v177, v179
	v_pk_mul_f32 v[82:83], v[82:83], v[158:159]
	v_max_f32_e32 v158, 0.5, v152
	v_cvt_f32_ubyte1_e32 v152, v153
	v_max_f32_e32 v159, 0.5, v152
	v_cvt_f32_ubyte2_e32 v152, v153
	v_cvt_f32_ubyte3_e32 v153, v153
	v_max_f32_e32 v152, 0.5, v152
	v_max_f32_e32 v153, 0.5, v153
	v_pk_mul_f32 v[152:153], v[152:153], v[176:177]
	global_load_dwordx2 v[176:177], v[160:161], off offset:3072
	global_load_dwordx2 v[178:179], v[160:161], off offset:1024
	v_max_f32_e32 v154, 0.5, v154
	v_max_f32_e32 v155, 0.5, v155
	v_pk_mul_f32 v[150:151], v[154:155], v[150:151]
	v_max_f32_e32 v170, 0.5, v170
	v_pk_mul_f32 v[72:73], v[72:73], v[150:151]
	v_pk_mul_f32 v[150:151], v[158:159], v[168:169]
	v_rcp_f32_e32 v170, v170
	v_pk_mul_f32 v[68:69], v[68:69], v[150:151]
	v_add_u32_e32 v150, 16, v1
	v_mad_i64_i32 v[150:151], s[4:5], v150, s33, v[148:149]
	v_rcp_f32_e32 v171, v171
	v_lshl_add_u64 v[150:151], v[150:151], 0, s[56:57]
	v_lshl_add_u64 v[150:151], v[150:151], 0, v[2:3]
	v_pk_mul_f32 v[70:71], v[70:71], v[152:153]
	v_lshl_add_u64 v[152:153], v[150:151], 0, s[64:65]
	v_add_co_u32_e32 v150, vcc, s12, v150
	v_max_f32_e32 v156, 0.5, v156
	s_nop 0
	v_addc_co_u32_e32 v151, vcc, 0, v151, vcc
	v_pk_mul_f32 v[154:155], v[156:157], v[170:171]
	global_load_dwordx2 v[184:185], v[150:151], off
	global_load_dwordx2 v[186:187], v[152:153], off offset:2048
	global_load_dwordx2 v[168:169], v[152:153], off offset:3072
	global_load_dwordx2 v[170:171], v[152:153], off offset:1024
	v_add_u32_e32 v150, 32, v1
	v_mad_i64_i32 v[150:151], s[4:5], v150, s33, v[148:149]
	v_lshl_add_u64 v[150:151], v[150:151], 0, s[56:57]
	v_lshl_add_u64 v[150:151], v[150:151], 0, v[2:3]
	v_lshl_add_u64 v[152:153], v[150:151], 0, s[64:65]
	v_add_co_u32_e32 v150, vcc, s12, v150
	v_pk_mul_f32 v[74:75], v[74:75], v[154:155]
	s_nop 0
	v_addc_co_u32_e32 v151, vcc, 0, v151, vcc
	global_load_dwordx2 v[160:161], v[150:151], off
	global_load_dwordx2 v[158:159], v[152:153], off offset:2048
	global_load_dwordx2 v[154:155], v[152:153], off offset:3072
	global_load_dwordx2 v[156:157], v[152:153], off offset:1024
	v_add_u32_e32 v1, 48, v1
	v_mad_i64_i32 v[148:149], s[4:5], v1, s33, v[148:149]
	v_lshl_add_u64 v[148:149], v[148:149], 0, s[56:57]
	v_lshl_add_u64 v[2:3], v[148:149], 0, v[2:3]
	v_lshl_add_u64 v[148:149], v[2:3], 0, s[64:65]
	v_add_co_u32_e32 v2, vcc, s12, v2
	v_addc_co_u32_e32 v3, vcc, 0, v3, vcc
	global_load_dwordx2 v[152:153], v[2:3], off
	global_load_dwordx2 v[150:151], v[148:149], off offset:2048
	s_nop 0
	global_load_dwordx2 v[2:3], v[148:149], off offset:3072
	s_nop 0
	global_load_dwordx2 v[148:149], v[148:149], off offset:1024
	s_waitcnt vmcnt(4)
	v_cvt_f32_ubyte0_e32 v1, v172
	v_max_f32_e32 v208, 0.5, v1
	v_cvt_f32_ubyte1_e32 v1, v172
	v_max_f32_e32 v209, 0.5, v1
	v_cvt_f32_ubyte2_e32 v1, v172
	v_max_f32_e32 v210, 0.5, v1
	v_cvt_f32_ubyte3_e32 v1, v172
	v_max_f32_e32 v211, 0.5, v1
	v_cvt_f32_ubyte0_e32 v1, v173
	v_max_f32_e32 v212, 0.5, v1
	v_cvt_f32_ubyte1_e32 v1, v173
	v_max_f32_e32 v213, 0.5, v1
	v_cvt_f32_ubyte2_e32 v1, v173
	v_max_f32_e32 v172, 0.5, v1
	v_cvt_f32_ubyte3_e32 v1, v173
	v_cvt_f32_ubyte1_e32 v214, v174
	v_max_f32_e32 v173, 0.5, v1
	v_cvt_f32_ubyte0_e32 v1, v174
	v_max_f32_e32 v215, 0.5, v214
	v_cvt_f32_ubyte2_e32 v214, v174
	v_cvt_f32_ubyte3_e32 v174, v174
	v_max_f32_e32 v217, 0.5, v174
	v_cvt_f32_ubyte0_e32 v174, v175
	v_max_f32_e32 v216, 0.5, v214
	v_max_f32_e32 v214, 0.5, v174
	v_cvt_f32_ubyte1_e32 v174, v175
	v_max_f32_e32 v218, 0.5, v174
	v_cvt_f32_ubyte2_e32 v174, v175
	v_max_f32_e32 v219, 0.5, v174
	v_cvt_f32_ubyte3_e32 v174, v175
	v_max_f32_e32 v220, 0.5, v174
	v_max_f32_e32 v1, 0.5, v1
	v_rcp_f32_e32 v175, v215
	v_rcp_f32_e32 v215, v218
	v_rcp_f32_e32 v218, v219
	v_rcp_f32_e32 v219, v220
	v_rcp_f32_e32 v174, v1
	v_rcp_f32_e32 v214, v214
	v_rcp_f32_e32 v216, v216
	v_rcp_f32_e32 v217, v217
	v_pk_mul_f32 v[172:173], v[172:173], v[218:219]
	v_cvt_f32_ubyte0_e32 v1, v178
	v_pk_mul_f32 v[174:175], v[208:209], v[174:175]
	v_pk_mul_f32 v[62:63], v[62:63], v[172:173]
	v_max_f32_e32 v172, 0.5, v1
	v_cvt_f32_ubyte1_e32 v1, v178
	v_pk_mul_f32 v[64:65], v[64:65], v[174:175]
	v_pk_mul_f32 v[174:175], v[212:213], v[214:215]
	v_max_f32_e32 v173, 0.5, v1
	v_cvt_f32_ubyte2_e32 v1, v178
	v_pk_mul_f32 v[60:61], v[60:61], v[174:175]
	v_max_f32_e32 v174, 0.5, v1
	v_cvt_f32_ubyte3_e32 v1, v178
	v_pk_mul_f32 v[208:209], v[210:211], v[216:217]
	v_max_f32_e32 v175, 0.5, v1
	v_cvt_f32_ubyte0_e32 v1, v179
	v_pk_mul_f32 v[66:67], v[66:67], v[208:209]
	v_max_f32_e32 v208, 0.5, v1
	v_cvt_f32_ubyte1_e32 v1, v179
	v_max_f32_e32 v209, 0.5, v1
	v_cvt_f32_ubyte2_e32 v1, v179
	v_max_f32_e32 v178, 0.5, v1
	v_cvt_f32_ubyte3_e32 v1, v179
	v_cvt_f32_ubyte1_e32 v210, v176
	v_max_f32_e32 v179, 0.5, v1
	v_cvt_f32_ubyte0_e32 v1, v176
	v_max_f32_e32 v211, 0.5, v210
	v_cvt_f32_ubyte2_e32 v210, v176
	v_cvt_f32_ubyte3_e32 v176, v176
	v_max_f32_e32 v213, 0.5, v176
	v_cvt_f32_ubyte0_e32 v176, v177
	v_max_f32_e32 v212, 0.5, v210
	v_max_f32_e32 v210, 0.5, v176
	v_cvt_f32_ubyte1_e32 v176, v177
	v_max_f32_e32 v214, 0.5, v176
	v_cvt_f32_ubyte2_e32 v176, v177
	v_max_f32_e32 v1, 0.5, v1
	v_max_f32_e32 v215, 0.5, v176
	v_cvt_f32_ubyte3_e32 v176, v177
	v_max_f32_e32 v216, 0.5, v176
	v_rcp_f32_e32 v176, v1
	v_rcp_f32_e32 v177, v211
	v_rcp_f32_e32 v210, v210
; __device__ __forceinline__ f32x4 un_unorm8(unsigned w) { return (f32x4){fmaxf((float)(w & 255u), 0.5f), fmaxf((float)((w >> 8) & 255u), 0.5f), fmaxf((float)((w >> 16) & 255u), 0.5f), fmaxf((float)(w >> 24), 0.5f)}; }
;     __device__ __forceinline__ void seam(f32x4 (&acc)[2][2][4][2], const Unit& u, int n, int wr, int wc, int fr, int fq) const {
;     ...
;             for (int m = 0; m < 4; ++m)
; #pragma unroll
;                 for (int bj = 0; bj < 2; ++bj) { const f32x4 a0 = un_unorm8(ga[m][bj].x), a1 = un_unorm8(ga[m][bj].y), b0 = un_unorm8(gb[m][bj].x), b1 = un_unorm8(gb[m][bj].y);
; #pragma unroll
;                     for (int j = 0; j < 4; ++j) { acc[ai][bj][m][0][j] *= a0[j] * __builtin_amdgcn_rcpf(b0[j]); acc[ai][bj][m][1][j] *= a1[j] * __builtin_amdgcn_rcpf(b1[j]); } }
	v_rcp_f32_e32 v211, v214
	v_rcp_f32_e32 v212, v212
	v_rcp_f32_e32 v213, v213
	v_rcp_f32_e32 v214, v215
	v_rcp_f32_e32 v215, v216
	v_pk_mul_f32 v[172:173], v[172:173], v[176:177]
	v_cvt_f32_ubyte0_e32 v1, v184
	v_pk_mul_f32 v[56:57], v[56:57], v[172:173]
	v_pk_mul_f32 v[172:173], v[208:209], v[210:211]
	v_pk_mul_f32 v[174:175], v[174:175], v[212:213]
	v_pk_mul_f32 v[52:53], v[52:53], v[172:173]
	v_max_f32_e32 v172, 0.5, v1
	v_cvt_f32_ubyte1_e32 v1, v184
	v_pk_mul_f32 v[58:59], v[58:59], v[174:175]
	v_pk_mul_f32 v[174:175], v[178:179], v[214:215]
	v_max_f32_e32 v173, 0.5, v1
	v_cvt_f32_ubyte2_e32 v1, v184
	v_pk_mul_f32 v[54:55], v[54:55], v[174:175]
	v_max_f32_e32 v174, 0.5, v1
	v_cvt_f32_ubyte3_e32 v1, v184
	v_max_f32_e32 v175, 0.5, v1
	v_cvt_f32_ubyte0_e32 v1, v185
	v_max_f32_e32 v176, 0.5, v1
	v_cvt_f32_ubyte1_e32 v1, v185
	v_max_f32_e32 v177, 0.5, v1
	v_cvt_f32_ubyte2_e32 v1, v185
	v_cvt_f32_ubyte1_e32 v184, v186
	v_max_f32_e32 v178, 0.5, v1
	v_cvt_f32_ubyte3_e32 v1, v185
	v_max_f32_e32 v185, 0.5, v184
	v_cvt_f32_ubyte2_e32 v184, v186
	v_max_f32_e32 v208, 0.5, v184
	v_cvt_f32_ubyte3_e32 v184, v186
	v_max_f32_e32 v209, 0.5, v184
	v_cvt_f32_ubyte0_e32 v184, v187
	v_max_f32_e32 v179, 0.5, v1
	v_cvt_f32_ubyte0_e32 v1, v186
	v_max_f32_e32 v186, 0.5, v184
	v_cvt_f32_ubyte1_e32 v184, v187
	v_max_f32_e32 v210, 0.5, v184
	v_cvt_f32_ubyte2_e32 v184, v187
	v_max_f32_e32 v1, 0.5, v1
	v_max_f32_e32 v211, 0.5, v184
	v_cvt_f32_ubyte3_e32 v184, v187
	v_max_f32_e32 v212, 0.5, v184
	v_rcp_f32_e32 v184, v1
	v_rcp_f32_e32 v185, v185
	v_rcp_f32_e32 v186, v186
	v_rcp_f32_e32 v187, v210
	v_rcp_f32_e32 v208, v208
	v_rcp_f32_e32 v209, v209
	v_rcp_f32_e32 v210, v211
	v_rcp_f32_e32 v211, v212
	v_pk_mul_f32 v[172:173], v[172:173], v[184:185]
	v_cvt_f32_ubyte0_e32 v1, v170
	v_pk_mul_f32 v[48:49], v[48:49], v[172:173]
	v_pk_mul_f32 v[172:173], v[176:177], v[186:187]
	v_pk_mul_f32 v[174:175], v[174:175], v[208:209]
	v_pk_mul_f32 v[44:45], v[44:45], v[172:173]
	v_max_f32_e32 v172, 0.5, v1
	v_cvt_f32_ubyte1_e32 v1, v170
	v_pk_mul_f32 v[50:51], v[50:51], v[174:175]
	v_pk_mul_f32 v[174:175], v[178:179], v[210:211]
	v_max_f32_e32 v173, 0.5, v1
	v_cvt_f32_ubyte2_e32 v1, v170
	v_pk_mul_f32 v[46:47], v[46:47], v[174:175]
	v_max_f32_e32 v174, 0.5, v1
	v_cvt_f32_ubyte3_e32 v1, v170
	v_max_f32_e32 v175, 0.5, v1
	v_cvt_f32_ubyte0_e32 v1, v171
	v_max_f32_e32 v176, 0.5, v1
	v_cvt_f32_ubyte1_e32 v1, v171
	v_max_f32_e32 v177, 0.5, v1
	v_cvt_f32_ubyte2_e32 v1, v171
	v_max_f32_e32 v170, 0.5, v1
	v_cvt_f32_ubyte3_e32 v1, v171
	v_cvt_f32_ubyte1_e32 v178, v168
	v_max_f32_e32 v171, 0.5, v1
	v_cvt_f32_ubyte0_e32 v1, v168
	v_max_f32_e32 v179, 0.5, v178
	v_cvt_f32_ubyte2_e32 v178, v168
	v_cvt_f32_ubyte3_e32 v168, v168
	v_max_f32_e32 v185, 0.5, v168
	v_cvt_f32_ubyte0_e32 v168, v169
	v_max_f32_e32 v184, 0.5, v178
	v_max_f32_e32 v178, 0.5, v168
	v_cvt_f32_ubyte1_e32 v168, v169
	v_max_f32_e32 v186, 0.5, v168
	v_cvt_f32_ubyte2_e32 v168, v169
	v_max_f32_e32 v1, 0.5, v1
	v_max_f32_e32 v187, 0.5, v168
	v_cvt_f32_ubyte3_e32 v168, v169
	v_max_f32_e32 v208, 0.5, v168
	v_rcp_f32_e32 v168, v1
	v_rcp_f32_e32 v169, v179
	v_rcp_f32_e32 v178, v178
	v_rcp_f32_e32 v179, v186
	v_rcp_f32_e32 v186, v187
	v_rcp_f32_e32 v187, v208
	v_pk_mul_f32 v[168:169], v[172:173], v[168:169]
	v_rcp_f32_e32 v184, v184
	v_rcp_f32_e32 v185, v185
	v_pk_mul_f32 v[40:41], v[40:41], v[168:169]
	v_pk_mul_f32 v[168:169], v[176:177], v[178:179]
	v_cvt_f32_ubyte0_e32 v1, v160
	v_pk_mul_f32 v[36:37], v[36:37], v[168:169]
	v_max_f32_e32 v168, 0.5, v1
	v_cvt_f32_ubyte1_e32 v1, v160
	v_pk_mul_f32 v[170:171], v[170:171], v[186:187]
	v_max_f32_e32 v169, 0.5, v1
	v_cvt_f32_ubyte2_e32 v1, v160
	v_pk_mul_f32 v[38:39], v[38:39], v[170:171]
	v_max_f32_e32 v170, 0.5, v1
	v_cvt_f32_ubyte3_e32 v1, v160
	v_pk_mul_f32 v[172:173], v[174:175], v[184:185]
	v_max_f32_e32 v171, 0.5, v1
	v_cvt_f32_ubyte0_e32 v1, v161
	v_pk_mul_f32 v[42:43], v[42:43], v[172:173]
	v_max_f32_e32 v172, 0.5, v1
	v_cvt_f32_ubyte1_e32 v1, v161
	v_max_f32_e32 v173, 0.5, v1
	v_cvt_f32_ubyte2_e32 v1, v161
	v_max_f32_e32 v160, 0.5, v1
	v_cvt_f32_ubyte3_e32 v1, v161
	v_cvt_f32_ubyte1_e32 v174, v158
	v_max_f32_e32 v161, 0.5, v1
	v_cvt_f32_ubyte0_e32 v1, v158
	v_max_f32_e32 v175, 0.5, v174
	v_cvt_f32_ubyte2_e32 v174, v158
	v_cvt_f32_ubyte3_e32 v158, v158
	v_max_f32_e32 v177, 0.5, v158
	v_cvt_f32_ubyte0_e32 v158, v159
	v_max_f32_e32 v176, 0.5, v174
	v_max_f32_e32 v174, 0.5, v158
	v_cvt_f32_ubyte1_e32 v158, v159
	v_max_f32_e32 v178, 0.5, v158
	v_cvt_f32_ubyte2_e32 v158, v159
	v_max_f32_e32 v1, 0.5, v1
	v_max_f32_e32 v179, 0.5, v158
	v_cvt_f32_ubyte3_e32 v158, v159
	v_max_f32_e32 v184, 0.5, v158
	v_rcp_f32_e32 v158, v1
	v_rcp_f32_e32 v159, v175
	v_rcp_f32_e32 v174, v174
	v_rcp_f32_e32 v175, v178
	v_rcp_f32_e32 v178, v179
	v_rcp_f32_e32 v179, v184
	v_pk_mul_f32 v[158:159], v[168:169], v[158:159]
	v_rcp_f32_e32 v176, v176
	v_rcp_f32_e32 v177, v177
	v_pk_mul_f32 v[32:33], v[32:33], v[158:159]
	v_pk_mul_f32 v[158:159], v[172:173], v[174:175]
	v_cvt_f32_ubyte0_e32 v1, v156
	v_pk_mul_f32 v[28:29], v[28:29], v[158:159]
	v_max_f32_e32 v158, 0.5, v1
	v_cvt_f32_ubyte1_e32 v1, v156
	v_pk_mul_f32 v[160:161], v[160:161], v[178:179]
	v_max_f32_e32 v159, 0.5, v1
	v_cvt_f32_ubyte2_e32 v1, v156
	v_pk_mul_f32 v[30:31], v[30:31], v[160:161]
	v_max_f32_e32 v160, 0.5, v1
	v_cvt_f32_ubyte3_e32 v1, v156
	v_pk_mul_f32 v[168:169], v[170:171], v[176:177]
	v_max_f32_e32 v161, 0.5, v1
	v_cvt_f32_ubyte0_e32 v1, v157
	v_pk_mul_f32 v[34:35], v[34:35], v[168:169]
	v_max_f32_e32 v168, 0.5, v1
	v_cvt_f32_ubyte1_e32 v1, v157
	v_max_f32_e32 v169, 0.5, v1
	v_cvt_f32_ubyte2_e32 v1, v157
	v_max_f32_e32 v156, 0.5, v1
	v_cvt_f32_ubyte3_e32 v1, v157
	v_cvt_f32_ubyte1_e32 v170, v154
	v_max_f32_e32 v157, 0.5, v1
	v_cvt_f32_ubyte0_e32 v1, v154
	v_max_f32_e32 v171, 0.5, v170
	v_cvt_f32_ubyte2_e32 v170, v154
	v_cvt_f32_ubyte3_e32 v154, v154
	v_max_f32_e32 v173, 0.5, v154
	v_cvt_f32_ubyte0_e32 v154, v155
	v_max_f32_e32 v172, 0.5, v170
	v_max_f32_e32 v170, 0.5, v154
	v_cvt_f32_ubyte1_e32 v154, v155
	v_max_f32_e32 v174, 0.5, v154
	v_cvt_f32_ubyte2_e32 v154, v155
	v_max_f32_e32 v1, 0.5, v1
	v_max_f32_e32 v175, 0.5, v154
	v_cvt_f32_ubyte3_e32 v154, v155
	v_max_f32_e32 v176, 0.5, v154
	v_rcp_f32_e32 v154, v1
	v_rcp_f32_e32 v155, v171
	v_rcp_f32_e32 v170, v170
	v_rcp_f32_e32 v171, v174
	v_rcp_f32_e32 v174, v175
	v_rcp_f32_e32 v175, v176
	v_pk_mul_f32 v[154:155], v[158:159], v[154:155]
	v_rcp_f32_e32 v172, v172
	v_rcp_f32_e32 v173, v173
	v_pk_mul_f32 v[24:25], v[24:25], v[154:155]
	v_pk_mul_f32 v[154:155], v[168:169], v[170:171]
	s_waitcnt vmcnt(0)
; __device__ __forceinline__ f32x4 un_unorm8(unsigned w) { return (f32x4){fmaxf((float)(w & 255u), 0.5f), fmaxf((float)((w >> 8) & 255u), 0.5f), fmaxf((float)((w >> 16) & 255u), 0.5f), fmaxf((float)(w >> 24), 0.5f)}; }
;     __device__ __forceinline__ void seam(f32x4 (&acc)[2][2][4][2], const Unit& u, int n, int wr, int wc, int fr, int fq) const {
;     ...
;             for (int m = 0; m < 4; ++m)
; #pragma unroll
;                 for (int bj = 0; bj < 2; ++bj) { const f32x4 a0 = un_unorm8(ga[m][bj].x), a1 = un_unorm8(ga[m][bj].y), b0 = un_unorm8(gb[m][bj].x), b1 = un_unorm8(gb[m][bj].y);
; #pragma unroll
;                     for (int j = 0; j < 4; ++j) { acc[ai][bj][m][0][j] *= a0[j] * __builtin_amdgcn_rcpf(b0[j]); acc[ai][bj][m][1][j] *= a1[j] * __builtin_amdgcn_rcpf(b1[j]); } }
;             asm volatile("" ::: "memory");
;         }
	v_cvt_f32_ubyte0_e32 v1, v152
	v_pk_mul_f32 v[20:21], v[20:21], v[154:155]
	v_max_f32_e32 v154, 0.5, v1
	v_cvt_f32_ubyte1_e32 v1, v152
	v_pk_mul_f32 v[156:157], v[156:157], v[174:175]
	v_max_f32_e32 v155, 0.5, v1
	v_cvt_f32_ubyte2_e32 v1, v152
	v_pk_mul_f32 v[22:23], v[22:23], v[156:157]
	v_max_f32_e32 v156, 0.5, v1
	v_cvt_f32_ubyte3_e32 v1, v152
	v_pk_mul_f32 v[158:159], v[160:161], v[172:173]
	v_max_f32_e32 v157, 0.5, v1
	v_cvt_f32_ubyte0_e32 v1, v153
	v_pk_mul_f32 v[26:27], v[26:27], v[158:159]
	v_max_f32_e32 v158, 0.5, v1
	v_cvt_f32_ubyte1_e32 v1, v153
	v_max_f32_e32 v159, 0.5, v1
	v_cvt_f32_ubyte2_e32 v1, v153
	v_max_f32_e32 v152, 0.5, v1
	v_cvt_f32_ubyte3_e32 v1, v153
	v_cvt_f32_ubyte1_e32 v160, v150
	v_max_f32_e32 v153, 0.5, v1
	v_cvt_f32_ubyte0_e32 v1, v150
	v_max_f32_e32 v161, 0.5, v160
	v_cvt_f32_ubyte2_e32 v160, v150
	v_cvt_f32_ubyte3_e32 v150, v150
	v_max_f32_e32 v169, 0.5, v150
	v_cvt_f32_ubyte0_e32 v150, v151
	v_max_f32_e32 v168, 0.5, v160
	v_max_f32_e32 v160, 0.5, v150
	v_cvt_f32_ubyte1_e32 v150, v151
	v_max_f32_e32 v170, 0.5, v150
	v_cvt_f32_ubyte2_e32 v150, v151
	v_max_f32_e32 v1, 0.5, v1
	v_max_f32_e32 v171, 0.5, v150
	v_cvt_f32_ubyte3_e32 v150, v151
	v_max_f32_e32 v172, 0.5, v150
	v_rcp_f32_e32 v150, v1
	v_rcp_f32_e32 v151, v161
	v_rcp_f32_e32 v160, v160
	v_rcp_f32_e32 v161, v170
	v_rcp_f32_e32 v170, v171
	v_rcp_f32_e32 v171, v172
	v_pk_mul_f32 v[150:151], v[154:155], v[150:151]
	v_rcp_f32_e32 v168, v168
	v_rcp_f32_e32 v169, v169
	v_pk_mul_f32 v[16:17], v[16:17], v[150:151]
	v_pk_mul_f32 v[150:151], v[158:159], v[160:161]
	v_cvt_f32_ubyte0_e32 v1, v148
	v_pk_mul_f32 v[12:13], v[12:13], v[150:151]
	v_max_f32_e32 v150, 0.5, v1
	v_cvt_f32_ubyte1_e32 v1, v148
	v_pk_mul_f32 v[152:153], v[152:153], v[170:171]
	v_max_f32_e32 v151, 0.5, v1
	v_cvt_f32_ubyte2_e32 v1, v148
	v_pk_mul_f32 v[14:15], v[14:15], v[152:153]
	v_max_f32_e32 v152, 0.5, v1
	v_cvt_f32_ubyte3_e32 v1, v148
	v_pk_mul_f32 v[154:155], v[156:157], v[168:169]
	v_max_f32_e32 v153, 0.5, v1
	v_cvt_f32_ubyte0_e32 v1, v149
	v_pk_mul_f32 v[18:19], v[18:19], v[154:155]
	v_max_f32_e32 v154, 0.5, v1
	v_cvt_f32_ubyte1_e32 v1, v149
	v_max_f32_e32 v155, 0.5, v1
	v_cvt_f32_ubyte2_e32 v1, v149
	v_max_f32_e32 v148, 0.5, v1
	v_cvt_f32_ubyte3_e32 v1, v149
	v_cvt_f32_ubyte1_e32 v156, v2
	v_max_f32_e32 v149, 0.5, v1
	v_cvt_f32_ubyte0_e32 v1, v2
	v_max_f32_e32 v157, 0.5, v156
	v_cvt_f32_ubyte2_e32 v156, v2
	v_cvt_f32_ubyte3_e32 v2, v2
	v_max_f32_e32 v159, 0.5, v2
	v_cvt_f32_ubyte0_e32 v2, v3
	v_max_f32_e32 v158, 0.5, v156
	v_max_f32_e32 v156, 0.5, v2
	v_cvt_f32_ubyte1_e32 v2, v3
	v_max_f32_e32 v160, 0.5, v2
	v_cvt_f32_ubyte2_e32 v2, v3
	v_max_f32_e32 v1, 0.5, v1
	v_max_f32_e32 v161, 0.5, v2
	v_cvt_f32_ubyte3_e32 v2, v3
	v_max_f32_e32 v168, 0.5, v2
	v_rcp_f32_e32 v2, v1
	v_rcp_f32_e32 v3, v157
	v_rcp_f32_e32 v156, v156
	v_rcp_f32_e32 v158, v158
	v_rcp_f32_e32 v159, v159
	v_rcp_f32_e32 v157, v160
	v_rcp_f32_e32 v160, v161
	v_rcp_f32_e32 v161, v168
	v_pk_mul_f32 v[2:3], v[150:151], v[2:3]
	v_pk_mul_f32 v[150:151], v[152:153], v[158:159]
	v_pk_mul_f32 v[8:9], v[8:9], v[2:3]
	v_pk_mul_f32 v[2:3], v[154:155], v[156:157]
	v_pk_mul_f32 v[148:149], v[148:149], v[160:161]
	v_pk_mul_f32 v[10:11], v[10:11], v[150:151]
	v_pk_mul_f32 v[6:7], v[6:7], v[148:149]
	v_pk_mul_f32 v[4:5], v[4:5], v[2:3]
	s_andn2_b64 vcc, exec, s[44:45]
	s_cbranch_vccnz .Lsm_b
	s_barrier
